# EpiResid epilogues (ffdown0/1, odout, ev_out): accumulator tile staged through a wave-private LDS strip; xin loads and X stores are dwordx4 row chunks instead of dword per lane
# speedup vs baseline: 1.0275x; 1.0007x over previous
.Leo_epi:
	v_lshl_or_b32 v87, v183, 3, v191
	v_lshrrev_b32_e32 v85, 6, v87
	v_and_b32_e32 v87, 63, v87
	s_nop 1
	v_readfirstlane_b32 s15, v85
	v_lshlrev_b32_e32 v85, 10, v85
	v_add_u32_e32 v85, 0x10000, v85
	v_and_b32_e32 v84, 31, v87
	v_lshl_add_u32 v84, v84, 2, v85
	v_lshrrev_b32_e32 v80, 5, v87
	v_lshl_add_u32 v84, v80, 9, v84
	v_lshl_add_u32 v85, v87, 4, v85
	v_and_b32_e32 v80, 7, v87
	v_lshlrev_b32_e32 v80, 4, v80
	v_lshrrev_b32_e32 v87, 3, v87
	v_lshl_add_u32 v87, v87, 12, v80
	s_and_b32 s101, s15, 1
	s_mul_i32 s101, s101, 128
	s_lshl_b32 s100, s11, 2
	s_add_u32 s101, s101, s100
	s_sub_u32 s100, s10, 0x2000
	s_lshr_b32 s100, s100, 11
	s_add_u32 s100, s100, 1
	s_cmp_lt_u32 s10, 0x2000
	s_cmov_b32 s100, 0
	s_mul_i32 s100, s100, 0x6000
	s_add_u32 s100, s100, s101
	s_add_u32 s100, s100, 0x3442000
	s_add_u32 s16, s90, s100
	s_addc_u32 s17, s91, 0
	global_load_dwordx4 v[80:83], v80, s[16:17]
	s_lshr_b32 s100, s15, 1
	s_lshl_b32 s100, s100, 6
	s_add_u32 s100, s100, s10
	s_sub_u32 s15, s100, 0x2000
	s_cmp_lt_u32 s10, 0x2000
	s_cselect_b32 s15, s100, s15
	s_cselect_b32 s16, s72, s74
	s_cselect_b32 s17, s73, s75
	s_lshl_b32 s15, s15, 12
	s_add_u32 s15, s15, s101
	s_add_u32 s16, s16, s15
	s_addc_u32 s17, s17, 0
	s_lshl_b32 s100, s100, 12
	s_add_u32 s100, s100, s101
	s_add_u32 s98, s88, s100
	s_addc_u32 s99, s89, 0
	global_load_dwordx4 v[96:99], v87, s[16:17]
	s_add_u32 s16, s16, 0x8000
	s_addc_u32 s17, s17, 0
	global_load_dwordx4 v[100:103], v87, s[16:17]
	s_add_u32 s16, s16, 0x8000
	s_addc_u32 s17, s17, 0
	global_load_dwordx4 v[104:107], v87, s[16:17]
	s_add_u32 s16, s16, 0x8000
	s_addc_u32 s17, s17, 0
	global_load_dwordx4 v[108:111], v87, s[16:17]
	s_add_u32 s16, s16, 0x8000
	s_addc_u32 s17, s17, 0
	global_load_dwordx4 v[112:115], v87, s[16:17]
	s_add_u32 s16, s16, 0x8000
	s_addc_u32 s17, s17, 0
	global_load_dwordx4 v[116:119], v87, s[16:17]
	s_add_u32 s16, s16, 0x8000
	s_addc_u32 s17, s17, 0
	global_load_dwordx4 v[120:123], v87, s[16:17]
	s_add_u32 s16, s16, 0x8000
	s_addc_u32 s17, s17, 0
	global_load_dwordx4 v[124:127], v87, s[16:17]
	ds_write_b32 v84, v0
	ds_write_b32 v84, v1 offset:128
	ds_write_b32 v84, v2 offset:256
	ds_write_b32 v84, v3 offset:384
	ds_read_b128 v[0:3], v85
	ds_write_b32 v84, v4
	ds_write_b32 v84, v5 offset:128
	ds_write_b32 v84, v6 offset:256
	ds_write_b32 v84, v7 offset:384
	ds_read_b128 v[4:7], v85
	ds_write_b32 v84, v8
	ds_write_b32 v84, v9 offset:128
	ds_write_b32 v84, v10 offset:256
	ds_write_b32 v84, v11 offset:384
	ds_read_b128 v[8:11], v85
	ds_write_b32 v84, v12
	ds_write_b32 v84, v13 offset:128
	ds_write_b32 v84, v14 offset:256
	ds_write_b32 v84, v15 offset:384
	ds_read_b128 v[12:15], v85
	ds_write_b32 v84, v16
	ds_write_b32 v84, v17 offset:128
	ds_write_b32 v84, v18 offset:256
	ds_write_b32 v84, v19 offset:384
	ds_read_b128 v[16:19], v85
	ds_write_b32 v84, v20
	ds_write_b32 v84, v21 offset:128
	ds_write_b32 v84, v22 offset:256
	ds_write_b32 v84, v23 offset:384
	ds_read_b128 v[20:23], v85
	ds_write_b32 v84, v24
	ds_write_b32 v84, v25 offset:128
	ds_write_b32 v84, v26 offset:256
	ds_write_b32 v84, v27 offset:384
	ds_read_b128 v[24:27], v85
	ds_write_b32 v84, v28
	ds_write_b32 v84, v29 offset:128
	ds_write_b32 v84, v30 offset:256
	ds_write_b32 v84, v31 offset:384
	ds_read_b128 v[28:31], v85
	s_waitcnt vmcnt(0) lgkmcnt(0)
	v_fmac_f32_e32 v96, v80, v0
	v_fmac_f32_e32 v97, v81, v1
	v_fmac_f32_e32 v98, v82, v2
	v_fmac_f32_e32 v99, v83, v3
	v_fmac_f32_e32 v100, v80, v4
	v_fmac_f32_e32 v101, v81, v5
	v_fmac_f32_e32 v102, v82, v6
	v_fmac_f32_e32 v103, v83, v7
	v_fmac_f32_e32 v104, v80, v8
	v_fmac_f32_e32 v105, v81, v9
	v_fmac_f32_e32 v106, v82, v10
	v_fmac_f32_e32 v107, v83, v11
	v_fmac_f32_e32 v108, v80, v12
	v_fmac_f32_e32 v109, v81, v13
	v_fmac_f32_e32 v110, v82, v14
	v_fmac_f32_e32 v111, v83, v15
	v_fmac_f32_e32 v112, v80, v16
	v_fmac_f32_e32 v113, v81, v17
	v_fmac_f32_e32 v114, v82, v18
	v_fmac_f32_e32 v115, v83, v19
	v_fmac_f32_e32 v116, v80, v20
	v_fmac_f32_e32 v117, v81, v21
	v_fmac_f32_e32 v118, v82, v22
	v_fmac_f32_e32 v119, v83, v23
	v_fmac_f32_e32 v120, v80, v24
	v_fmac_f32_e32 v121, v81, v25
	v_fmac_f32_e32 v122, v82, v26
	v_fmac_f32_e32 v123, v83, v27
	v_fmac_f32_e32 v124, v80, v28
	v_fmac_f32_e32 v125, v81, v29
	v_fmac_f32_e32 v126, v82, v30
	v_fmac_f32_e32 v127, v83, v31
	global_store_dwordx4 v87, v[96:99], s[98:99]
	s_add_u32 s98, s98, 0x8000
	s_addc_u32 s99, s99, 0
	global_store_dwordx4 v87, v[100:103], s[98:99]
	s_add_u32 s98, s98, 0x8000
	s_addc_u32 s99, s99, 0
	global_store_dwordx4 v87, v[104:107], s[98:99]
	s_add_u32 s98, s98, 0x8000
	s_addc_u32 s99, s99, 0
	global_store_dwordx4 v87, v[108:111], s[98:99]
	s_add_u32 s98, s98, 0x8000
	s_addc_u32 s99, s99, 0
	global_store_dwordx4 v87, v[112:115], s[98:99]
	s_add_u32 s98, s98, 0x8000
	s_addc_u32 s99, s99, 0
	global_store_dwordx4 v87, v[116:119], s[98:99]
	s_add_u32 s98, s98, 0x8000
	s_addc_u32 s99, s99, 0
	global_store_dwordx4 v87, v[120:123], s[98:99]
	s_add_u32 s98, s98, 0x8000
	s_addc_u32 s99, s99, 0
	global_store_dwordx4 v87, v[124:127], s[98:99]
	s_branch .Leo_next

.LBB0_1107:
	s_and_b64 vcc, exec, s[36:37]
	s_cbranch_vccnz .Leps3_partpath
	v_lshl_or_b32 v254, v183, 3, v191
	v_lshrrev_b32_e32 v253, 6, v254
	v_and_b32_e32 v254, 63, v254
	s_nop 1
	v_readfirstlane_b32 s7, v253
	v_lshlrev_b32_e32 v253, 10, v253
	v_add_u32_e32 v253, 0x10000, v253
	v_and_b32_e32 v252, 31, v254
	v_lshl_add_u32 v252, v252, 2, v253
	v_lshrrev_b32_e32 v138, 5, v254
	v_lshl_add_u32 v252, v138, 9, v252
	v_lshl_add_u32 v253, v254, 4, v253
	v_and_b32_e32 v138, 7, v254
	v_lshlrev_b32_e32 v138, 4, v138
	v_lshrrev_b32_e32 v254, 3, v254
	v_lshl_add_u32 v254, v254, 12, v138
	s_and_b32 s101, s7, 1
	s_mul_i32 s101, s101, 256
	s_lshl_b32 s100, s10, 2
	s_add_u32 s101, s101, s100
	s_sub_u32 s100, s9, 0x2000
	s_lshr_b32 s100, s100, 11
	s_add_u32 s100, s100, 1
	s_cmp_lt_u32 s9, 0x2000
	s_cmov_b32 s100, 0
	s_mul_i32 s100, s100, 0x6000
	s_add_u32 s100, s100, s101
	s_add_u32 s100, s100, 0x3445000
	s_add_u32 s2, s90, s100
	s_addc_u32 s3, s91, 0
	v_mov_b32_e32 v255, v138
	global_load_dwordx4 v[142:145], v255, s[2:3] offset:128
	global_load_dwordx4 v[138:141], v255, s[2:3]
	s_lshr_b32 s100, s7, 1
	s_lshl_b32 s100, s100, 6
	s_add_u32 s100, s100, s9
	s_lshl_b32 s100, s100, 12
	s_add_u32 s100, s100, s101
	s_add_u32 s98, s88, s100
	s_addc_u32 s99, s89, 0
	s_mov_b32 s2, s98
	s_mov_b32 s3, s99
	global_load_dwordx4 v[64:67], v254, s[2:3]
	global_load_dwordx4 v[68:71], v254, s[2:3] offset:128
	s_add_u32 s2, s2, 0x8000
	s_addc_u32 s3, s3, 0
	global_load_dwordx4 v[72:75], v254, s[2:3]
	global_load_dwordx4 v[76:79], v254, s[2:3] offset:128
	s_add_u32 s2, s2, 0x8000
	s_addc_u32 s3, s3, 0
	global_load_dwordx4 v[80:83], v254, s[2:3]
	global_load_dwordx4 v[84:87], v254, s[2:3] offset:128
	s_add_u32 s2, s2, 0x8000
	s_addc_u32 s3, s3, 0
	global_load_dwordx4 v[88:91], v254, s[2:3]
	global_load_dwordx4 v[92:95], v254, s[2:3] offset:128
	s_add_u32 s2, s2, 0x8000
	s_addc_u32 s3, s3, 0
	global_load_dwordx4 v[96:99], v254, s[2:3]
	global_load_dwordx4 v[100:103], v254, s[2:3] offset:128
	s_add_u32 s2, s2, 0x8000
	s_addc_u32 s3, s3, 0
	global_load_dwordx4 v[104:107], v254, s[2:3]
	global_load_dwordx4 v[108:111], v254, s[2:3] offset:128
	s_add_u32 s2, s2, 0x8000
	s_addc_u32 s3, s3, 0
	global_load_dwordx4 v[112:115], v254, s[2:3]
	global_load_dwordx4 v[116:119], v254, s[2:3] offset:128
	s_add_u32 s2, s2, 0x8000
	s_addc_u32 s3, s3, 0
	global_load_dwordx4 v[120:123], v254, s[2:3]
	global_load_dwordx4 v[124:127], v254, s[2:3] offset:128
	ds_write_b32 v252, v48
	ds_write_b32 v252, v49 offset:128
	ds_write_b32 v252, v50 offset:256
	ds_write_b32 v252, v51 offset:384
	ds_read_b128 v[48:51], v253
	ds_write_b32 v252, v16
	ds_write_b32 v252, v17 offset:128
	ds_write_b32 v252, v18 offset:256
	ds_write_b32 v252, v19 offset:384
	ds_read_b128 v[16:19], v253
	ds_write_b32 v252, v52
	ds_write_b32 v252, v53 offset:128
	ds_write_b32 v252, v54 offset:256
	ds_write_b32 v252, v55 offset:384
	ds_read_b128 v[52:55], v253
	ds_write_b32 v252, v20
	ds_write_b32 v252, v21 offset:128
	ds_write_b32 v252, v22 offset:256
	ds_write_b32 v252, v23 offset:384
	ds_read_b128 v[20:23], v253
	ds_write_b32 v252, v56
	ds_write_b32 v252, v57 offset:128
	ds_write_b32 v252, v58 offset:256
	ds_write_b32 v252, v59 offset:384
	ds_read_b128 v[56:59], v253
	ds_write_b32 v252, v24
	ds_write_b32 v252, v25 offset:128
	ds_write_b32 v252, v26 offset:256
	ds_write_b32 v252, v27 offset:384
	ds_read_b128 v[24:27], v253
	ds_write_b32 v252, v60
	ds_write_b32 v252, v61 offset:128
	ds_write_b32 v252, v62 offset:256
	ds_write_b32 v252, v63 offset:384
	ds_read_b128 v[60:63], v253
	ds_write_b32 v252, v28
	ds_write_b32 v252, v29 offset:128
	ds_write_b32 v252, v30 offset:256
	ds_write_b32 v252, v31 offset:384
	ds_read_b128 v[28:31], v253
	ds_write_b32 v252, v32
	ds_write_b32 v252, v33 offset:128
	ds_write_b32 v252, v34 offset:256
	ds_write_b32 v252, v35 offset:384
	ds_read_b128 v[32:35], v253
	ds_write_b32 v252, v0
	ds_write_b32 v252, v1 offset:128
	ds_write_b32 v252, v2 offset:256
	ds_write_b32 v252, v3 offset:384
	ds_read_b128 v[0:3], v253
	ds_write_b32 v252, v36
	ds_write_b32 v252, v37 offset:128
	ds_write_b32 v252, v38 offset:256
	ds_write_b32 v252, v39 offset:384
	ds_read_b128 v[36:39], v253
	ds_write_b32 v252, v4
	ds_write_b32 v252, v5 offset:128
	ds_write_b32 v252, v6 offset:256
	ds_write_b32 v252, v7 offset:384
	ds_read_b128 v[4:7], v253
	ds_write_b32 v252, v40
	ds_write_b32 v252, v41 offset:128
	ds_write_b32 v252, v42 offset:256
	ds_write_b32 v252, v43 offset:384
	ds_read_b128 v[40:43], v253
	ds_write_b32 v252, v8
	ds_write_b32 v252, v9 offset:128
	ds_write_b32 v252, v10 offset:256
	ds_write_b32 v252, v11 offset:384
	ds_read_b128 v[8:11], v253
	ds_write_b32 v252, v44
	ds_write_b32 v252, v45 offset:128
	ds_write_b32 v252, v46 offset:256
	ds_write_b32 v252, v47 offset:384
	ds_read_b128 v[44:47], v253
	ds_write_b32 v252, v12
	ds_write_b32 v252, v13 offset:128
	ds_write_b32 v252, v14 offset:256
	ds_write_b32 v252, v15 offset:384
	ds_read_b128 v[12:15], v253
	s_waitcnt vmcnt(0) lgkmcnt(0)
	v_fmac_f32_e32 v64, v138, v48
	v_fmac_f32_e32 v65, v139, v49
	v_fmac_f32_e32 v66, v140, v50
	v_fmac_f32_e32 v67, v141, v51
	v_fmac_f32_e32 v68, v142, v16
	v_fmac_f32_e32 v69, v143, v17
	v_fmac_f32_e32 v70, v144, v18
	v_fmac_f32_e32 v71, v145, v19
	v_fmac_f32_e32 v72, v138, v52
	v_fmac_f32_e32 v73, v139, v53
	v_fmac_f32_e32 v74, v140, v54
	v_fmac_f32_e32 v75, v141, v55
	v_fmac_f32_e32 v76, v142, v20
	v_fmac_f32_e32 v77, v143, v21
	v_fmac_f32_e32 v78, v144, v22
	v_fmac_f32_e32 v79, v145, v23
	v_fmac_f32_e32 v80, v138, v56
	v_fmac_f32_e32 v81, v139, v57
	v_fmac_f32_e32 v82, v140, v58
	v_fmac_f32_e32 v83, v141, v59
	v_fmac_f32_e32 v84, v142, v24
	v_fmac_f32_e32 v85, v143, v25
	v_fmac_f32_e32 v86, v144, v26
	v_fmac_f32_e32 v87, v145, v27
	v_fmac_f32_e32 v88, v138, v60
	v_fmac_f32_e32 v89, v139, v61
	v_fmac_f32_e32 v90, v140, v62
	v_fmac_f32_e32 v91, v141, v63
	v_fmac_f32_e32 v92, v142, v28
	v_fmac_f32_e32 v93, v143, v29
	v_fmac_f32_e32 v94, v144, v30
	v_fmac_f32_e32 v95, v145, v31
	v_fmac_f32_e32 v96, v138, v32
	v_fmac_f32_e32 v97, v139, v33
	v_fmac_f32_e32 v98, v140, v34
	v_fmac_f32_e32 v99, v141, v35
	v_fmac_f32_e32 v100, v142, v0
	v_fmac_f32_e32 v101, v143, v1
	v_fmac_f32_e32 v102, v144, v2
	v_fmac_f32_e32 v103, v145, v3
	v_fmac_f32_e32 v104, v138, v36
	v_fmac_f32_e32 v105, v139, v37
	v_fmac_f32_e32 v106, v140, v38
	v_fmac_f32_e32 v107, v141, v39
	v_fmac_f32_e32 v108, v142, v4
	v_fmac_f32_e32 v109, v143, v5
	v_fmac_f32_e32 v110, v144, v6
	v_fmac_f32_e32 v111, v145, v7
	v_fmac_f32_e32 v112, v138, v40
	v_fmac_f32_e32 v113, v139, v41
	v_fmac_f32_e32 v114, v140, v42
	v_fmac_f32_e32 v115, v141, v43
	v_fmac_f32_e32 v116, v142, v8
	v_fmac_f32_e32 v117, v143, v9
	v_fmac_f32_e32 v118, v144, v10
	v_fmac_f32_e32 v119, v145, v11
	v_fmac_f32_e32 v120, v138, v44
	v_fmac_f32_e32 v121, v139, v45
	v_fmac_f32_e32 v122, v140, v46
	v_fmac_f32_e32 v123, v141, v47
	v_fmac_f32_e32 v124, v142, v12
	v_fmac_f32_e32 v125, v143, v13
	v_fmac_f32_e32 v126, v144, v14
	v_fmac_f32_e32 v127, v145, v15
	global_store_dwordx4 v254, v[64:67], s[98:99]
	global_store_dwordx4 v254, v[68:71], s[98:99] offset:128
	s_add_u32 s98, s98, 0x8000
	s_addc_u32 s99, s99, 0
	global_store_dwordx4 v254, v[72:75], s[98:99]
	global_store_dwordx4 v254, v[76:79], s[98:99] offset:128
	s_add_u32 s98, s98, 0x8000
	s_addc_u32 s99, s99, 0
	global_store_dwordx4 v254, v[80:83], s[98:99]
	global_store_dwordx4 v254, v[84:87], s[98:99] offset:128
	s_add_u32 s98, s98, 0x8000
	s_addc_u32 s99, s99, 0
	global_store_dwordx4 v254, v[88:91], s[98:99]
	global_store_dwordx4 v254, v[92:95], s[98:99] offset:128
	s_add_u32 s98, s98, 0x8000
	s_addc_u32 s99, s99, 0
	global_store_dwordx4 v254, v[96:99], s[98:99]
	global_store_dwordx4 v254, v[100:103], s[98:99] offset:128
	s_add_u32 s98, s98, 0x8000
	s_addc_u32 s99, s99, 0
	global_store_dwordx4 v254, v[104:107], s[98:99]
	global_store_dwordx4 v254, v[108:111], s[98:99] offset:128
	s_add_u32 s98, s98, 0x8000
	s_addc_u32 s99, s99, 0
	global_store_dwordx4 v254, v[112:115], s[98:99]
	global_store_dwordx4 v254, v[116:119], s[98:99] offset:128
	s_add_u32 s98, s98, 0x8000
	s_addc_u32 s99, s99, 0
	global_store_dwordx4 v254, v[120:123], s[98:99]
	global_store_dwordx4 v254, v[124:127], s[98:99] offset:128
	s_branch .LBB0_1098

.LBB0_1882:
	s_and_b64 vcc, exec, s[36:37]
	s_cbranch_vccnz .Leps5_partpath
	v_lshl_or_b32 v254, v183, 3, v191
	v_lshrrev_b32_e32 v253, 6, v254
	v_and_b32_e32 v254, 63, v254
	s_nop 1
	v_readfirstlane_b32 s7, v253
	v_lshlrev_b32_e32 v253, 10, v253
	v_add_u32_e32 v253, 0x10000, v253
	v_and_b32_e32 v252, 31, v254
	v_lshl_add_u32 v252, v252, 2, v253
	v_lshrrev_b32_e32 v136, 5, v254
	v_lshl_add_u32 v252, v136, 9, v252
	v_lshl_add_u32 v253, v254, 4, v253
	v_and_b32_e32 v136, 7, v254
	v_lshlrev_b32_e32 v136, 4, v136
	v_lshrrev_b32_e32 v254, 3, v254
	v_lshl_add_u32 v254, v254, 12, v136
	s_and_b32 s101, s7, 1
	s_mul_i32 s101, s101, 256
	s_lshl_b32 s100, s10, 2
	s_add_u32 s101, s101, s100
	s_sub_u32 s100, s9, 0x2000
	s_lshr_b32 s100, s100, 11
	s_add_u32 s100, s100, 1
	s_cmp_lt_u32 s9, 0x2000
	s_cmov_b32 s100, 0
	s_mul_i32 s100, s100, 0x6000
	s_add_u32 s100, s100, s101
	s_add_u32 s100, s100, 0x3454000
	s_add_u32 s4, s90, s100
	s_addc_u32 s5, s91, 0
	v_mov_b32_e32 v255, v136
	global_load_dwordx4 v[140:143], v255, s[4:5] offset:128
	global_load_dwordx4 v[136:139], v255, s[4:5]
	s_lshr_b32 s100, s7, 1
	s_lshl_b32 s100, s100, 6
	s_add_u32 s100, s100, s9
	s_lshl_b32 s100, s100, 12
	s_add_u32 s100, s100, s101
	s_add_u32 s98, s88, s100
	s_addc_u32 s99, s89, 0
	s_mov_b32 s4, s98
	s_mov_b32 s5, s99
	global_load_dwordx4 v[64:67], v254, s[4:5]
	global_load_dwordx4 v[68:71], v254, s[4:5] offset:128
	s_add_u32 s4, s4, 0x8000
	s_addc_u32 s5, s5, 0
	global_load_dwordx4 v[72:75], v254, s[4:5]
	global_load_dwordx4 v[76:79], v254, s[4:5] offset:128
	s_add_u32 s4, s4, 0x8000
	s_addc_u32 s5, s5, 0
	global_load_dwordx4 v[80:83], v254, s[4:5]
	global_load_dwordx4 v[84:87], v254, s[4:5] offset:128
	s_add_u32 s4, s4, 0x8000
	s_addc_u32 s5, s5, 0
	global_load_dwordx4 v[88:91], v254, s[4:5]
	global_load_dwordx4 v[92:95], v254, s[4:5] offset:128
	s_add_u32 s4, s4, 0x8000
	s_addc_u32 s5, s5, 0
	global_load_dwordx4 v[96:99], v254, s[4:5]
	global_load_dwordx4 v[100:103], v254, s[4:5] offset:128
	s_add_u32 s4, s4, 0x8000
	s_addc_u32 s5, s5, 0
	global_load_dwordx4 v[104:107], v254, s[4:5]
	global_load_dwordx4 v[108:111], v254, s[4:5] offset:128
	s_add_u32 s4, s4, 0x8000
	s_addc_u32 s5, s5, 0
	global_load_dwordx4 v[112:115], v254, s[4:5]
	global_load_dwordx4 v[116:119], v254, s[4:5] offset:128
	s_add_u32 s4, s4, 0x8000
	s_addc_u32 s5, s5, 0
	global_load_dwordx4 v[120:123], v254, s[4:5]
	global_load_dwordx4 v[124:127], v254, s[4:5] offset:128
	ds_write_b32 v252, v48
	ds_write_b32 v252, v49 offset:128
	ds_write_b32 v252, v50 offset:256
	ds_write_b32 v252, v51 offset:384
	ds_read_b128 v[48:51], v253
	ds_write_b32 v252, v16
	ds_write_b32 v252, v17 offset:128
	ds_write_b32 v252, v18 offset:256
	ds_write_b32 v252, v19 offset:384
	ds_read_b128 v[16:19], v253
	ds_write_b32 v252, v52
	ds_write_b32 v252, v53 offset:128
	ds_write_b32 v252, v54 offset:256
	ds_write_b32 v252, v55 offset:384
	ds_read_b128 v[52:55], v253
	ds_write_b32 v252, v20
	ds_write_b32 v252, v21 offset:128
	ds_write_b32 v252, v22 offset:256
	ds_write_b32 v252, v23 offset:384
	ds_read_b128 v[20:23], v253
	ds_write_b32 v252, v56
	ds_write_b32 v252, v57 offset:128
	ds_write_b32 v252, v58 offset:256
	ds_write_b32 v252, v59 offset:384
	ds_read_b128 v[56:59], v253
	ds_write_b32 v252, v24
	ds_write_b32 v252, v25 offset:128
	ds_write_b32 v252, v26 offset:256
	ds_write_b32 v252, v27 offset:384
	ds_read_b128 v[24:27], v253
	ds_write_b32 v252, v60
	ds_write_b32 v252, v61 offset:128
	ds_write_b32 v252, v62 offset:256
	ds_write_b32 v252, v63 offset:384
	ds_read_b128 v[60:63], v253
	ds_write_b32 v252, v28
	ds_write_b32 v252, v29 offset:128
	ds_write_b32 v252, v30 offset:256
	ds_write_b32 v252, v31 offset:384
	ds_read_b128 v[28:31], v253
	ds_write_b32 v252, v32
	ds_write_b32 v252, v33 offset:128
	ds_write_b32 v252, v34 offset:256
	ds_write_b32 v252, v35 offset:384
	ds_read_b128 v[32:35], v253
	ds_write_b32 v252, v0
	ds_write_b32 v252, v1 offset:128
	ds_write_b32 v252, v2 offset:256
	ds_write_b32 v252, v3 offset:384
	ds_read_b128 v[0:3], v253
	ds_write_b32 v252, v36
	ds_write_b32 v252, v37 offset:128
	ds_write_b32 v252, v38 offset:256
	ds_write_b32 v252, v39 offset:384
	ds_read_b128 v[36:39], v253
	ds_write_b32 v252, v4
	ds_write_b32 v252, v5 offset:128
	ds_write_b32 v252, v6 offset:256
	ds_write_b32 v252, v7 offset:384
	ds_read_b128 v[4:7], v253
	ds_write_b32 v252, v40
	ds_write_b32 v252, v41 offset:128
	ds_write_b32 v252, v42 offset:256
	ds_write_b32 v252, v43 offset:384
	ds_read_b128 v[40:43], v253
	ds_write_b32 v252, v8
	ds_write_b32 v252, v9 offset:128
	ds_write_b32 v252, v10 offset:256
	ds_write_b32 v252, v11 offset:384
	ds_read_b128 v[8:11], v253
	ds_write_b32 v252, v44
	ds_write_b32 v252, v45 offset:128
	ds_write_b32 v252, v46 offset:256
	ds_write_b32 v252, v47 offset:384
	ds_read_b128 v[44:47], v253
	ds_write_b32 v252, v12
	ds_write_b32 v252, v13 offset:128
	ds_write_b32 v252, v14 offset:256
	ds_write_b32 v252, v15 offset:384
	ds_read_b128 v[12:15], v253
	s_waitcnt vmcnt(0) lgkmcnt(0)
	v_fmac_f32_e32 v64, v136, v48
	v_fmac_f32_e32 v65, v137, v49
	v_fmac_f32_e32 v66, v138, v50
	v_fmac_f32_e32 v67, v139, v51
	v_fmac_f32_e32 v68, v140, v16
	v_fmac_f32_e32 v69, v141, v17
	v_fmac_f32_e32 v70, v142, v18
	v_fmac_f32_e32 v71, v143, v19
	v_fmac_f32_e32 v72, v136, v52
	v_fmac_f32_e32 v73, v137, v53
	v_fmac_f32_e32 v74, v138, v54
	v_fmac_f32_e32 v75, v139, v55
	v_fmac_f32_e32 v76, v140, v20
	v_fmac_f32_e32 v77, v141, v21
	v_fmac_f32_e32 v78, v142, v22
	v_fmac_f32_e32 v79, v143, v23
	v_fmac_f32_e32 v80, v136, v56
	v_fmac_f32_e32 v81, v137, v57
	v_fmac_f32_e32 v82, v138, v58
	v_fmac_f32_e32 v83, v139, v59
	v_fmac_f32_e32 v84, v140, v24
	v_fmac_f32_e32 v85, v141, v25
	v_fmac_f32_e32 v86, v142, v26
	v_fmac_f32_e32 v87, v143, v27
	v_fmac_f32_e32 v88, v136, v60
	v_fmac_f32_e32 v89, v137, v61
	v_fmac_f32_e32 v90, v138, v62
	v_fmac_f32_e32 v91, v139, v63
	v_fmac_f32_e32 v92, v140, v28
	v_fmac_f32_e32 v93, v141, v29
	v_fmac_f32_e32 v94, v142, v30
	v_fmac_f32_e32 v95, v143, v31
	v_fmac_f32_e32 v96, v136, v32
	v_fmac_f32_e32 v97, v137, v33
	v_fmac_f32_e32 v98, v138, v34
	v_fmac_f32_e32 v99, v139, v35
	v_fmac_f32_e32 v100, v140, v0
	v_fmac_f32_e32 v101, v141, v1
	v_fmac_f32_e32 v102, v142, v2
	v_fmac_f32_e32 v103, v143, v3
	v_fmac_f32_e32 v104, v136, v36
	v_fmac_f32_e32 v105, v137, v37
	v_fmac_f32_e32 v106, v138, v38
	v_fmac_f32_e32 v107, v139, v39
	v_fmac_f32_e32 v108, v140, v4
	v_fmac_f32_e32 v109, v141, v5
	v_fmac_f32_e32 v110, v142, v6
	v_fmac_f32_e32 v111, v143, v7
	v_fmac_f32_e32 v112, v136, v40
	v_fmac_f32_e32 v113, v137, v41
	v_fmac_f32_e32 v114, v138, v42
	v_fmac_f32_e32 v115, v139, v43
	v_fmac_f32_e32 v116, v140, v8
	v_fmac_f32_e32 v117, v141, v9
	v_fmac_f32_e32 v118, v142, v10
	v_fmac_f32_e32 v119, v143, v11
	v_fmac_f32_e32 v120, v136, v44
	v_fmac_f32_e32 v121, v137, v45
	v_fmac_f32_e32 v122, v138, v46
	v_fmac_f32_e32 v123, v139, v47
	v_fmac_f32_e32 v124, v140, v12
	v_fmac_f32_e32 v125, v141, v13
	v_fmac_f32_e32 v126, v142, v14
	v_fmac_f32_e32 v127, v143, v15
	global_store_dwordx4 v254, v[64:67], s[98:99]
	global_store_dwordx4 v254, v[68:71], s[98:99] offset:128
	s_add_u32 s98, s98, 0x8000
	s_addc_u32 s99, s99, 0
	global_store_dwordx4 v254, v[72:75], s[98:99]
	global_store_dwordx4 v254, v[76:79], s[98:99] offset:128
	s_add_u32 s98, s98, 0x8000
	s_addc_u32 s99, s99, 0
	global_store_dwordx4 v254, v[80:83], s[98:99]
	global_store_dwordx4 v254, v[84:87], s[98:99] offset:128
	s_add_u32 s98, s98, 0x8000
	s_addc_u32 s99, s99, 0
	global_store_dwordx4 v254, v[88:91], s[98:99]
	global_store_dwordx4 v254, v[92:95], s[98:99] offset:128
	s_add_u32 s98, s98, 0x8000
	s_addc_u32 s99, s99, 0
	global_store_dwordx4 v254, v[96:99], s[98:99]
	global_store_dwordx4 v254, v[100:103], s[98:99] offset:128
	s_add_u32 s98, s98, 0x8000
	s_addc_u32 s99, s99, 0
	global_store_dwordx4 v254, v[104:107], s[98:99]
	global_store_dwordx4 v254, v[108:111], s[98:99] offset:128
	s_add_u32 s98, s98, 0x8000
	s_addc_u32 s99, s99, 0
	global_store_dwordx4 v254, v[112:115], s[98:99]
	global_store_dwordx4 v254, v[116:119], s[98:99] offset:128
	s_add_u32 s98, s98, 0x8000
	s_addc_u32 s99, s99, 0
	global_store_dwordx4 v254, v[120:123], s[98:99]
	global_store_dwordx4 v254, v[124:127], s[98:99] offset:128
	s_branch .LBB0_1873

.LBB0_2356:
	s_and_b64 vcc, exec, s[26:27]
	s_cbranch_vccnz .Leps7_partpath
	v_lshl_or_b32 v254, v183, 3, v191
	v_lshrrev_b32_e32 v253, 6, v254
	v_and_b32_e32 v254, 63, v254
	s_nop 1
	v_readfirstlane_b32 s5, v253
	v_lshlrev_b32_e32 v253, 10, v253
	v_add_u32_e32 v253, 0x10000, v253
	v_and_b32_e32 v252, 31, v254
	v_lshl_add_u32 v252, v252, 2, v253
	v_lshrrev_b32_e32 v134, 5, v254
	v_lshl_add_u32 v252, v134, 9, v252
	v_lshl_add_u32 v253, v254, 4, v253
	v_and_b32_e32 v134, 7, v254
	v_lshlrev_b32_e32 v134, 4, v134
	v_lshrrev_b32_e32 v254, 3, v254
	v_lshl_add_u32 v254, v254, 12, v134
	s_and_b32 s101, s5, 1
	s_mul_i32 s101, s101, 256
	s_lshl_b32 s100, s8, 2
	s_add_u32 s101, s101, s100
	s_sub_u32 s100, s7, 0x2000
	s_lshr_b32 s100, s100, 11
	s_add_u32 s100, s100, 1
	s_cmp_lt_u32 s7, 0x2000
	s_cmov_b32 s100, 0
	s_mul_i32 s100, s100, 0x6000
	s_add_u32 s100, s100, s101
	s_add_u32 s100, s100, 0x3457000
	s_add_u32 s2, s90, s100
	s_addc_u32 s3, s91, 0
	v_mov_b32_e32 v255, v134
	global_load_dwordx4 v[138:141], v255, s[2:3] offset:128
	global_load_dwordx4 v[134:137], v255, s[2:3]
	s_lshr_b32 s100, s5, 1
	s_lshl_b32 s100, s100, 6
	s_add_u32 s100, s100, s7
	s_lshl_b32 s100, s100, 12
	s_add_u32 s100, s100, s101
	s_add_u32 s98, s88, s100
	s_addc_u32 s99, s89, 0
	s_mov_b32 s2, s98
	s_mov_b32 s3, s99
	global_load_dwordx4 v[64:67], v254, s[2:3]
	global_load_dwordx4 v[68:71], v254, s[2:3] offset:128
	s_add_u32 s2, s2, 0x8000
	s_addc_u32 s3, s3, 0
	global_load_dwordx4 v[72:75], v254, s[2:3]
	global_load_dwordx4 v[76:79], v254, s[2:3] offset:128
	s_add_u32 s2, s2, 0x8000
	s_addc_u32 s3, s3, 0
	global_load_dwordx4 v[80:83], v254, s[2:3]
	global_load_dwordx4 v[84:87], v254, s[2:3] offset:128
	s_add_u32 s2, s2, 0x8000
	s_addc_u32 s3, s3, 0
	global_load_dwordx4 v[88:91], v254, s[2:3]
	global_load_dwordx4 v[92:95], v254, s[2:3] offset:128
	s_add_u32 s2, s2, 0x8000
	s_addc_u32 s3, s3, 0
	global_load_dwordx4 v[96:99], v254, s[2:3]
	global_load_dwordx4 v[100:103], v254, s[2:3] offset:128
	s_add_u32 s2, s2, 0x8000
	s_addc_u32 s3, s3, 0
	global_load_dwordx4 v[104:107], v254, s[2:3]
	global_load_dwordx4 v[108:111], v254, s[2:3] offset:128
	s_add_u32 s2, s2, 0x8000
	s_addc_u32 s3, s3, 0
	global_load_dwordx4 v[112:115], v254, s[2:3]
	global_load_dwordx4 v[116:119], v254, s[2:3] offset:128
	s_add_u32 s2, s2, 0x8000
	s_addc_u32 s3, s3, 0
	global_load_dwordx4 v[120:123], v254, s[2:3]
	global_load_dwordx4 v[124:127], v254, s[2:3] offset:128
	ds_write_b32 v252, v48
	ds_write_b32 v252, v49 offset:128
	ds_write_b32 v252, v50 offset:256
	ds_write_b32 v252, v51 offset:384
	ds_read_b128 v[48:51], v253
	ds_write_b32 v252, v16
	ds_write_b32 v252, v17 offset:128
	ds_write_b32 v252, v18 offset:256
	ds_write_b32 v252, v19 offset:384
	ds_read_b128 v[16:19], v253
	ds_write_b32 v252, v52
	ds_write_b32 v252, v53 offset:128
	ds_write_b32 v252, v54 offset:256
	ds_write_b32 v252, v55 offset:384
	ds_read_b128 v[52:55], v253
	ds_write_b32 v252, v20
	ds_write_b32 v252, v21 offset:128
	ds_write_b32 v252, v22 offset:256
	ds_write_b32 v252, v23 offset:384
	ds_read_b128 v[20:23], v253
	ds_write_b32 v252, v56
	ds_write_b32 v252, v57 offset:128
	ds_write_b32 v252, v58 offset:256
	ds_write_b32 v252, v59 offset:384
	ds_read_b128 v[56:59], v253
	ds_write_b32 v252, v24
	ds_write_b32 v252, v25 offset:128
	ds_write_b32 v252, v26 offset:256
	ds_write_b32 v252, v27 offset:384
	ds_read_b128 v[24:27], v253
	ds_write_b32 v252, v60
	ds_write_b32 v252, v61 offset:128
	ds_write_b32 v252, v62 offset:256
	ds_write_b32 v252, v63 offset:384
	ds_read_b128 v[60:63], v253
	ds_write_b32 v252, v28
	ds_write_b32 v252, v29 offset:128
	ds_write_b32 v252, v30 offset:256
	ds_write_b32 v252, v31 offset:384
	ds_read_b128 v[28:31], v253
	ds_write_b32 v252, v32
	ds_write_b32 v252, v33 offset:128
	ds_write_b32 v252, v34 offset:256
	ds_write_b32 v252, v35 offset:384
	ds_read_b128 v[32:35], v253
	ds_write_b32 v252, v0
	ds_write_b32 v252, v1 offset:128
	ds_write_b32 v252, v2 offset:256
	ds_write_b32 v252, v3 offset:384
	ds_read_b128 v[0:3], v253
	ds_write_b32 v252, v36
	ds_write_b32 v252, v37 offset:128
	ds_write_b32 v252, v38 offset:256
	ds_write_b32 v252, v39 offset:384
	ds_read_b128 v[36:39], v253
	ds_write_b32 v252, v4
	ds_write_b32 v252, v5 offset:128
	ds_write_b32 v252, v6 offset:256
	ds_write_b32 v252, v7 offset:384
	ds_read_b128 v[4:7], v253
	ds_write_b32 v252, v40
	ds_write_b32 v252, v41 offset:128
	ds_write_b32 v252, v42 offset:256
	ds_write_b32 v252, v43 offset:384
	ds_read_b128 v[40:43], v253
	ds_write_b32 v252, v8
	ds_write_b32 v252, v9 offset:128
	ds_write_b32 v252, v10 offset:256
	ds_write_b32 v252, v11 offset:384
	ds_read_b128 v[8:11], v253
	ds_write_b32 v252, v44
	ds_write_b32 v252, v45 offset:128
	ds_write_b32 v252, v46 offset:256
	ds_write_b32 v252, v47 offset:384
	ds_read_b128 v[44:47], v253
	ds_write_b32 v252, v12
	ds_write_b32 v252, v13 offset:128
	ds_write_b32 v252, v14 offset:256
	ds_write_b32 v252, v15 offset:384
	ds_read_b128 v[12:15], v253
	s_waitcnt vmcnt(0) lgkmcnt(0)
	v_fmac_f32_e32 v64, v134, v48
	v_fmac_f32_e32 v65, v135, v49
	v_fmac_f32_e32 v66, v136, v50
	v_fmac_f32_e32 v67, v137, v51
	v_fmac_f32_e32 v68, v138, v16
	v_fmac_f32_e32 v69, v139, v17
	v_fmac_f32_e32 v70, v140, v18
	v_fmac_f32_e32 v71, v141, v19
	v_fmac_f32_e32 v72, v134, v52
	v_fmac_f32_e32 v73, v135, v53
	v_fmac_f32_e32 v74, v136, v54
	v_fmac_f32_e32 v75, v137, v55
	v_fmac_f32_e32 v76, v138, v20
	v_fmac_f32_e32 v77, v139, v21
	v_fmac_f32_e32 v78, v140, v22
	v_fmac_f32_e32 v79, v141, v23
	v_fmac_f32_e32 v80, v134, v56
	v_fmac_f32_e32 v81, v135, v57
	v_fmac_f32_e32 v82, v136, v58
	v_fmac_f32_e32 v83, v137, v59
	v_fmac_f32_e32 v84, v138, v24
	v_fmac_f32_e32 v85, v139, v25
	v_fmac_f32_e32 v86, v140, v26
	v_fmac_f32_e32 v87, v141, v27
	v_fmac_f32_e32 v88, v134, v60
	v_fmac_f32_e32 v89, v135, v61
	v_fmac_f32_e32 v90, v136, v62
	v_fmac_f32_e32 v91, v137, v63
	v_fmac_f32_e32 v92, v138, v28
	v_fmac_f32_e32 v93, v139, v29
	v_fmac_f32_e32 v94, v140, v30
	v_fmac_f32_e32 v95, v141, v31
	v_fmac_f32_e32 v96, v134, v32
	v_fmac_f32_e32 v97, v135, v33
	v_fmac_f32_e32 v98, v136, v34
	v_fmac_f32_e32 v99, v137, v35
	v_fmac_f32_e32 v100, v138, v0
	v_fmac_f32_e32 v101, v139, v1
	v_fmac_f32_e32 v102, v140, v2
	v_fmac_f32_e32 v103, v141, v3
	v_fmac_f32_e32 v104, v134, v36
	v_fmac_f32_e32 v105, v135, v37
	v_fmac_f32_e32 v106, v136, v38
	v_fmac_f32_e32 v107, v137, v39
	v_fmac_f32_e32 v108, v138, v4
	v_fmac_f32_e32 v109, v139, v5
	v_fmac_f32_e32 v110, v140, v6
	v_fmac_f32_e32 v111, v141, v7
	v_fmac_f32_e32 v112, v134, v40
	v_fmac_f32_e32 v113, v135, v41
	v_fmac_f32_e32 v114, v136, v42
	v_fmac_f32_e32 v115, v137, v43
	v_fmac_f32_e32 v116, v138, v8
	v_fmac_f32_e32 v117, v139, v9
	v_fmac_f32_e32 v118, v140, v10
	v_fmac_f32_e32 v119, v141, v11
	v_fmac_f32_e32 v120, v134, v44
	v_fmac_f32_e32 v121, v135, v45
	v_fmac_f32_e32 v122, v136, v46
	v_fmac_f32_e32 v123, v137, v47
	v_fmac_f32_e32 v124, v138, v12
	v_fmac_f32_e32 v125, v139, v13
	v_fmac_f32_e32 v126, v140, v14
	v_fmac_f32_e32 v127, v141, v15
	global_store_dwordx4 v254, v[64:67], s[98:99]
	global_store_dwordx4 v254, v[68:71], s[98:99] offset:128
	s_add_u32 s98, s98, 0x8000
	s_addc_u32 s99, s99, 0
	global_store_dwordx4 v254, v[72:75], s[98:99]
	global_store_dwordx4 v254, v[76:79], s[98:99] offset:128
	s_add_u32 s98, s98, 0x8000
	s_addc_u32 s99, s99, 0
	global_store_dwordx4 v254, v[80:83], s[98:99]
	global_store_dwordx4 v254, v[84:87], s[98:99] offset:128
	s_add_u32 s98, s98, 0x8000
	s_addc_u32 s99, s99, 0
	global_store_dwordx4 v254, v[88:91], s[98:99]
	global_store_dwordx4 v254, v[92:95], s[98:99] offset:128
	s_add_u32 s98, s98, 0x8000
	s_addc_u32 s99, s99, 0
	global_store_dwordx4 v254, v[96:99], s[98:99]
	global_store_dwordx4 v254, v[100:103], s[98:99] offset:128
	s_add_u32 s98, s98, 0x8000
	s_addc_u32 s99, s99, 0
	global_store_dwordx4 v254, v[104:107], s[98:99]
	global_store_dwordx4 v254, v[108:111], s[98:99] offset:128
	s_add_u32 s98, s98, 0x8000
	s_addc_u32 s99, s99, 0
	global_store_dwordx4 v254, v[112:115], s[98:99]
	global_store_dwordx4 v254, v[116:119], s[98:99] offset:128
	s_add_u32 s98, s98, 0x8000
	s_addc_u32 s99, s99, 0
	global_store_dwordx4 v254, v[120:123], s[98:99]
	global_store_dwordx4 v254, v[124:127], s[98:99] offset:128
	s_branch .LBB0_2347
